# in-proj tiles computed by the XCD that owns the sequence (64 tiles per XCD) and XCD-local barrier in-proj -> mixer; only the ff2 -> next in-proj barrier (and prologue/final) remain global
# speedup vs baseline: 1.0338x; 1.0077x over previous
.Lmy_rank_skip:
	s_or_b64 exec, exec, s[60:61]
	s_waitcnt vmcnt(0) lgkmcnt(0)
	s_barrier
	v_mov_b32_e32 v1, 0x20040
	ds_read_b32 v1, v1
	v_readfirstlane_b32 s58, v0
	s_waitcnt lgkmcnt(0)
	v_readfirstlane_b32 s59, v1
	s_lshl_b32 s59, s59, 3
	s_add_i32 s59, s59, s71
	s_cmp_eq_u32 s58, 0
	s_cselect_b32 s2, s59, s2
	s_cselect_b32 s58, 1, 0
	s_nop 0
	v_writelane_b32 v255, s58, 46
	s_ashr_i32 s43, s2, 31
	s_lshr_b32 s0, s43, 29
	s_add_i32 s0, s2, s0
	s_and_b32 s1, s0, -8
	s_sub_i32 s1, s2, s1
	s_add_i32 s4, s76, 0xfffffa00
	s_cmp_lt_i32 s1, 0
	s_movk_i32 s7, 0x61
	s_cselect_b32 s5, 45, 44
	s_cselect_b32 s6, 25, 24
	s_cselect_b32 s7, s7, 0x60
	s_cmpk_gt_i32 s42, 0xc0
	s_cselect_b32 s33, s4, s76
	s_add_i32 s4, s42, 0xffffff40
	s_cmpk_gt_i32 s42, 0xc0
	s_cselect_b32 s63, s4, s42
	s_add_i32 s4, s2, 0xffffff40
	s_mov_b32 s8, s76
	s_cmpk_gt_i32 s42, 0xc0
	v_writelane_b32 v254, s8, 17
	s_cselect_b32 s13, s4, s2
	s_cmpk_lt_i32 s2, 0x200
	v_writelane_b32 v254, s9, 18
	s_cselect_b64 s[8:9], -1, 0
	v_writelane_b32 v254, s8, 19
	s_add_i32 s4, s2, 0xa0
	s_bfe_u32 s4, s4, 0x50003
	v_writelane_b32 v254, s9, 20
	s_and_b32 s8, s2, 7
	s_mul_i32 s8, s8, 20
	s_add_i32 s4, s4, s8
	s_mul_i32 s8, s4, 0xcd
	s_bfe_u32 s8, s8, 0x3000d
	s_mul_i32 s9, s8, 40
	s_mul_i32 s5, s5, s1
	s_sub_i32 s9, s4, s9
	s_ashr_i32 s4, s0, 3
	s_add_i32 s5, s5, s4
	s_mul_hi_i32 s0, s5, 0x2e8ba2e9
	s_lshr_b32 s11, s0, 31
	s_ashr_i32 s0, s0, 4
	s_add_i32 s0, s0, s11
	s_mul_i32 s11, s0, 0x58
	s_sub_i32 s5, s5, s11
	s_bfe_i32 s11, s5, 0x80000
	s_bfe_u32 s11, s11, 0x3000c
	s_add_i32 s11, s5, s11
	s_bfe_i32 s12, s11, 0x80000
	s_and_b32 s11, s11, 0xf8
	s_lshl_b32 s8, s8, 2
	s_sub_i32 s5, s5, s11
	s_and_b32 s10, s8, 28
	s_lshl_b32 s0, s0, 3
	s_sext_i32_i8 s5, s5
	s_sub_i32 s10, 16, s10
	s_sext_i32_i16 s12, s12
	s_add_i32 s0, s0, s5
	s_min_u32 s10, s10, 4
	s_ashr_i32 s11, s12, 3
	s_add_i32 s0, s0, 16
	s_ashr_i32 s51, s42, 31
	s_add_u32 s48, s38, 0x4820000
	s_addc_u32 s49, s39, 0
	s_add_u32 s50, s38, 0x3820000
	s_addc_u32 s68, s39, 0
	s_add_u32 s69, s38, 0x5820000
	s_addc_u32 s62, s39, 0
	v_writelane_b32 v254, s11, 21
	s_add_u32 s14, s40, 0x4200
	v_writelane_b32 v254, s0, 22
	s_addc_u32 s15, s41, 0
	v_writelane_b32 v254, s14, 23
	s_waitcnt lgkmcnt(0)
	v_cvt_f32_ubyte0_e32 v0, s10
	v_rcp_iflag_f32_e32 v1, v0
	v_writelane_b32 v254, s15, 24
	s_add_u32 s14, s40, 0x7400
	s_addc_u32 s15, s41, 0
	v_writelane_b32 v254, s14, 25
	v_cvt_f32_ubyte0_e32 v2, s9
	v_mul_f32_e32 v1, v2, v1
	v_writelane_b32 v254, s15, 26
	s_add_u32 s14, s40, 0x7500
	s_addc_u32 s15, s41, 0
	v_writelane_b32 v254, s14, 27
	s_add_u32 s0, s40, 0x2000
	v_trunc_f32_e32 v1, v1
	v_writelane_b32 v254, s15, 28
	v_writelane_b32 v254, s0, 29
	s_addc_u32 s0, s41, 0
	s_cmpk_lt_i32 s2, 0xc0
	v_writelane_b32 v254, s0, 30
	s_cselect_b64 s[14:15], -1, 0
	v_writelane_b32 v254, s14, 31
	s_cmp_lt_i32 s13, 0
	v_cvt_u32_f32_e32 v3, v1
	v_writelane_b32 v254, s15, 32
	s_cselect_b64 s[14:15], -1, 0
	v_writelane_b32 v254, s14, 33
	s_cmpk_lt_u32 s13, 0x6c
	v_fma_f32 v1, -v1, v0, v2
	v_writelane_b32 v254, s15, 34
	s_cselect_b64 s[14:15], -1, 0
	v_writelane_b32 v254, s14, 35
	s_add_u32 s0, s40, 0x400000
	s_mov_b32 s97, 0
	v_writelane_b32 v254, s15, 36
	v_writelane_b32 v254, s0, 37
	s_addc_u32 s0, s41, 0
	v_writelane_b32 v254, s0, 38
	s_add_u32 s0, s40, 0x300000
	v_writelane_b32 v254, s0, 39
	s_addc_u32 s0, s41, 0
	s_cmpk_lt_i32 s2, 0x300
	v_writelane_b32 v254, s0, 40
	s_cselect_b64 s[14:15], -1, 0
	v_writelane_b32 v254, s14, 41
	s_lshl_b32 s0, s13, 3
	v_mov_b32_e32 v65, 0
	v_writelane_b32 v254, s15, 42
	v_writelane_b32 v254, s0, 43
	s_add_u32 s0, s40, 0x4600000
	v_writelane_b32 v254, s0, 44
	s_addc_u32 s0, s41, 0
	v_writelane_b32 v254, s0, 45
	s_add_u32 s0, s40, 0x2600000
	v_writelane_b32 v254, s0, 46
	s_addc_u32 s0, s41, 0
	v_writelane_b32 v254, s0, 47
	s_add_u32 s0, s40, 0x1e00000
	v_writelane_b32 v254, s0, 48
	s_addc_u32 s0, s41, 0
	v_writelane_b32 v254, s0, 49
	s_add_u32 s0, s40, 0x800000
	v_writelane_b32 v254, s0, 50
	s_addc_u32 s0, s41, 0
	v_writelane_b32 v254, s0, 51
	s_add_i32 s0, s2, 0xfffffe00
	s_cmp_gt_u32 s0, 0xffffff5f
	s_mul_i32 s0, s1, s6
	s_cselect_b64 s[14:15], -1, 0
	s_add_i32 s0, s0, s4
	s_ashr_i32 s5, s0, 31
	s_lshr_b32 s5, s5, 27
	s_add_i32 s5, s0, s5
	s_ashr_i32 s6, s5, 5
	s_and_b32 s5, s5, 0xffe0
	s_sub_i32 s5, s0, s5
	s_bfe_i32 s0, s5, 0x80000
	s_bfe_u32 s0, s0, 0x3000c
	s_add_i32 s11, s5, s0
	s_mul_i32 s1, s1, s7
	s_bfe_i32 s0, s11, 0x80000
	s_and_b32 s11, s11, 0xf8
	s_add_i32 s1, s1, s4
	s_sub_i32 s5, s5, s11
	s_ashr_i32 s4, s1, 31
	v_writelane_b32 v254, s14, 52
	s_lshl_b32 s6, s6, 3
	s_sext_i32_i16 s12, s0
	s_sext_i32_i8 s5, s5
	s_lshr_b32 s4, s4, 25
	v_writelane_b32 v254, s15, 53
	s_add_i32 s14, s6, s5
	s_ashr_i32 s5, s12, 3
	s_add_i32 s4, s1, s4
	v_writelane_b32 v254, s5, 54
	s_ashr_i32 s5, s4, 7
	s_and_b32 s4, s4, 0xff80
	s_sub_i32 s1, s1, s4
	s_bfe_i32 s4, s1, 0x80000
	s_bfe_u32 s4, s4, 0x3000c
	s_add_i32 s6, s1, s4
	s_bfe_i32 s4, s6, 0x80000
	s_and_b32 s6, s6, 0xf8
	s_sub_i32 s1, s1, s6
	s_lshl_b32 s5, s5, 3
	s_sext_i32_i16 s7, s4
	s_sext_i32_i8 s1, s1
	s_add_i32 s16, s5, s1
	s_ashr_i32 s1, s7, 3
	v_writelane_b32 v254, s1, 55
	s_mov_b32 s6, s16
	s_lshr_b32 s4, s7, 3
	s_ashr_i32 s17, s16, 31
	v_writelane_b32 v254, s6, 56
	s_bfe_i64 s[4:5], s[4:5], 0x100000
	s_lshl_b64 s[4:5], s[4:5], 19
	v_writelane_b32 v254, s7, 57
	s_lshl_b64 s[6:7], s[16:17], 19
	v_writelane_b32 v254, s6, 58
	s_ashr_i32 s15, s14, 31
	s_lshr_b32 s0, s12, 3
	v_writelane_b32 v254, s7, 59
	v_writelane_b32 v254, s4, 60
	s_bfe_i64 s[0:1], s[0:1], 0x100000
	v_mov_b32_e32 v229, 0x358637bd
	v_writelane_b32 v254, s5, 61
	s_lshl_b64 s[4:5], s[14:15], 19
	v_writelane_b32 v254, s4, 62
	v_mov_b32_e32 v230, 1
	v_mov_b32_e32 v190, 0x3f4ccccd
	v_writelane_b32 v254, s5, 63
	s_lshl_b64 s[4:5], s[0:1], 19
	v_writelane_b32 v255, s4, 0
	s_lshl_b64 s[0:1], s[0:1], 21
	v_mov_b32_e32 v231, 0x1000
	v_writelane_b32 v255, s5, 1
	s_mov_b32 s4, s14
	v_writelane_b32 v255, s4, 2
	v_mov_b32_e32 v232, 0x3ecc95a3
	v_mov_b32_e32 v233, 0x3c088889
	v_writelane_b32 v255, s5, 3
	s_lshl_b64 s[4:5], s[14:15], 21
	v_writelane_b32 v255, s4, 4
	v_mov_b32_e32 v234, 0x7f800000
	v_mov_b32_e32 v235, 0x7fc00000
	v_writelane_b32 v255, s5, 5
	v_writelane_b32 v255, s0, 6
	v_readfirstlane_b32 s4, v3
	v_mov_b32_e32 v236, 0xff800000
	v_writelane_b32 v255, s1, 7
	v_cmp_ge_f32_e64 s[0:1], |v1|, v0
	s_cmp_lg_u64 s[0:1], 0
	s_addc_u32 s0, s4, 0
	s_mul_i32 s1, s0, s10
	s_sub_i32 s1, s9, s1
	s_add_i32 s1, s1, s8
	s_and_b32 s1, s1, 0xff
	s_and_b32 s4, s0, 0xff
	s_cmp_gt_u32 s4, 7
	v_writelane_b32 v255, s1, 8
	s_cselect_b64 s[0:1], -1, 0
	s_cmp_lg_u64 s[0:1], 0
	s_addc_u32 s0, s4, 0
	s_load_dwordx8 s[4:11], s[80:81], 0xd0
	v_writelane_b32 v255, s0, 9
	v_writelane_b32 v255, s13, 10
	s_lshl_b32 s0, s13, 6
	v_writelane_b32 v255, s0, 11
	s_addk_i32 s0, 0xf500
	s_lshl_b32 s79, s63, 6
	s_waitcnt lgkmcnt(0)
	s_mov_b64 s[4:5], s[8:9]
	v_writelane_b32 v255, s0, 12
	s_add_u32 s0, s4, 0x1000000
	s_addc_u32 s1, s5, 0
	v_writelane_b32 v255, s0, 13
	v_mov_b32_e32 v237, 0x3e800000
	v_bfrev_b32_e32 v238, 0.5
	v_writelane_b32 v255, s1, 14
	s_load_dwordx2 s[0:1], s[80:81], 0x68
	v_mov_b64_e32 v[192:193], 0xc0
	v_mov_b64_e32 v[194:195], 0xbf
	v_not_b32_e32 v239, 30
	s_mov_b32 s55, 0x800000
	s_waitcnt lgkmcnt(0)
	s_add_u32 s0, s0, 0xb00000
	s_addc_u32 s1, s1, 0
	v_writelane_b32 v255, s0, 15
	s_movk_i32 s92, 0x3ff
	s_movk_i32 s93, 0x1600
	v_writelane_b32 v255, s1, 16
	s_add_i32 s0, 0, 0x20020
	v_writelane_b32 v255, s0, 17
	s_add_i32 s0, 0, 0x20024
	v_writelane_b32 v255, s0, 18
	s_add_i32 s0, 0, 0x12200
	v_writelane_b32 v255, s0, 19
	s_add_i32 s0, 0, 0x15800
	v_writelane_b32 v255, s0, 20
	s_brev_b32 s0, 1
	v_writelane_b32 v255, s0, 21
	s_movk_i32 s94, 0x90
	s_movk_i32 s95, 0xf7
	v_writelane_b32 v255, s1, 22
	v_writelane_b32 v255, s2, 23
	v_writelane_b32 v255, s3, 24
	v_writelane_b32 v255, s80, 25
	s_movk_i32 s46, 0x7d0
	s_add_i32 s47, 0, 0x20000
	v_writelane_b32 v255, s81, 26
	v_writelane_b32 v255, s63, 27
	v_writelane_b32 v255, s79, 28
	s_mov_b32 s52, 0x41000000
	s_movk_i32 s54, 0xfeff
	s_mov_b32 s64, 0xc800
	s_mov_b32 s65, 0xbe800000
	s_movk_i32 s78, 0x2c00
	s_mov_b64 s[28:29], 0
	s_mov_b64 s[30:31], 0x80
	s_mov_b64 s[72:73], 0
	s_mov_b32 s74, s97
	s_and_b32 s58, s2, 7
	s_lshr_b32 s59, s2, 3
	s_mul_i32 s60, s59, 43
	s_lshr_b32 s60, s60, 8
	s_mul_i32 s61, s60, 6
	s_sub_i32 s59, s59, s61
	s_lshl_b32 s61, s58, 1
	s_add_i32 s61, s61, s59
	s_lshl_b32 s58, s58, 2
	s_add_i32 s58, s58, s59
	s_add_i32 s58, s58, 14
	s_cmp_lt_u32 s59, 2
	s_cselect_b32 s58, s61, s58
	s_mov_b32 s61, 0
	v_writelane_b32 v254, s60, 54
	v_writelane_b32 v254, s60, 55
	v_writelane_b32 v254, s58, 56
	v_writelane_b32 v254, s61, 57
	v_writelane_b32 v255, s58, 2
	v_writelane_b32 v255, s61, 3
	v_writelane_b32 v254, s61, 59
	v_writelane_b32 v254, s61, 61
	v_writelane_b32 v254, s61, 63
	v_writelane_b32 v255, s61, 1
	v_writelane_b32 v255, s61, 5
	v_writelane_b32 v255, s61, 7
	s_lshl_b32 s59, s58, 19
	v_writelane_b32 v254, s59, 58
	v_writelane_b32 v254, s59, 62
	s_lshl_b32 s59, s58, 21
	v_writelane_b32 v255, s59, 4
	s_lshl_b32 s59, s60, 19
	v_writelane_b32 v254, s59, 60
	v_writelane_b32 v255, s59, 0
	s_lshl_b32 s59, s60, 21
	v_writelane_b32 v255, s59, 6
	s_and_b32 s58, s2, 7
	s_lshr_b32 s59, s2, 3
	s_cmp_lt_u32 s59, 20
	s_cbranch_scc0 .Lmy_h_lat
	s_cmp_ge_u32 s59, 10
	s_cselect_b32 s60, 1, 0
	s_mul_i32 s61, s60, 10
	s_sub_i32 s61, s59, s61
	s_lshl_b32 s58, s58, 1
	s_add_i32 s60, s60, s58
	s_cmp_gt_u32 s61, 7
	s_addc_u32 s61, s61, 0
	s_branch .Lmy_h_done
.Lmy_h_lat:
	s_sub_i32 s59, s59, 20
	s_mul_i32 s60, s59, 47
	s_lshr_b32 s60, s60, 9
	s_mul_i32 s61, s60, 11
	s_sub_i32 s61, s59, s61
	s_lshl_b32 s58, s58, 2
	s_add_i32 s60, s60, s58
	s_add_i32 s60, s60, 16
.Lmy_h_done:
	v_writelane_b32 v254, s61, 21
	v_writelane_b32 v254, s60, 22
	v_writelane_b32 v255, s33, 29
	s_barrier
	s_mov_b64 s[6:7], s[10:11]
	s_branch .LBB0_455

.LBB0_463:
	s_add_i32 s63, s63, 1
	s_mul_i32 s1, s63, s51
	s_mul_hi_u32 s4, s63, s42
	s_add_i32 s4, s4, s1
	s_mul_i32 s1, s63, s42
	s_add_u32 s56, s1, s2
	s_addc_u32 s57, s4, s43
	v_mov_b64_e32 v[0:1], 0x200
	v_cmp_lt_i64_e64 s[4:5], s[56:57], v[0:1]
	v_mov_b64_e32 v[0:1], 0x1ff
	v_cmp_gt_i64_e32 vcc, s[56:57], v[0:1]
	s_cbranch_vccnz .LBB0_468
	s_and_b32 s1, s56, 7
	s_lshr_b32 s13, s56, 3
	s_cmp_lt_u32 s13, 20
	s_cbranch_scc0 .Lmy_in_lat
	s_cmp_ge_u32 s13, 10
	s_cselect_b32 s22, 1, 0
	s_mul_i32 s24, s22, 10
	s_sub_i32 s24, s13, s24
	s_lshl_b32 s1, s1, 1
	s_add_i32 s22, s22, s1
	s_cmp_gt_u32 s24, 7
	s_addc_u32 s24, s24, 0
	s_branch .LBB0_468
.Lmy_in_lat:
	s_sub_i32 s13, s13, 20
	s_mul_i32 s22, s13, 47
	s_lshr_b32 s22, s22, 9
	s_mul_i32 s24, s22, 11
	s_sub_i32 s24, s13, s24
	s_lshl_b32 s1, s1, 2
	s_add_i32 s22, s22, s1
	s_add_i32 s22, s22, 16

.LBB0_811:
	s_mov_b32 s6, s71
	s_waitcnt vmcnt(0)
	s_waitcnt lgkmcnt(0)
	s_barrier
	s_and_saveexec_b64 s[0:1], s[26:27]
	s_cbranch_execz .LBB0_848
	v_readlane_b32 s7, v255, 17
	s_waitcnt vmcnt(0) expcnt(0) lgkmcnt(0)
	s_mov_b64 s[4:5], exec
	v_mov_b32_e32 v0, s7
	v_readlane_b32 s7, v255, 18
	ds_read_b32 v2, v0
	v_mbcnt_lo_u32_b32 v1, s4, 0
	v_mov_b32_e32 v0, s7
	ds_read_b32 v0, v0
	v_mbcnt_hi_u32_b32 v1, s5, v1
	s_lshl_b32 s20, s6, 6
	v_cmp_eq_u32_e32 vcc, 0, v1
	s_and_saveexec_b64 s[6:7], vcc
	s_cbranch_execz .LBB0_814
	s_add_i32 s96, s20, 0x500
	v_readlane_b32 s8, v255, 46
	s_lshr_b32 s9, s20, 1
	s_add_i32 s9, s9, 0xe50
	s_cmp_lg_u32 s8, 0
	s_cselect_b32 s96, s9, s96
	s_lshl_b64 s[8:9], s[96:97], 2
	v_readlane_b32 s10, v254, 10
	v_readlane_b32 s11, v254, 11
	s_add_u32 s8, s10, s8
	s_addc_u32 s9, s11, s9
	s_bcnt1_i32_b64 s4, s[4:5]
	v_mov_b32_e32 v3, s4
	global_atomic_add v3, v65, v3, s[8:9] sc0
